# attn_out / four_out GEMM epilogues: gate/partial-sum loads issued up to 9-10 ahead by cloning their row-address computations into spare registers (counted vmcnt)
# speedup vs baseline: 1.0024x; 1.0024x over previous
.LBB0_1312:
	v_lshl_add_u32 v140, s5, 8, v143
	v_lshl_or_b32 v138, s4, 8, v145
	v_ashrrev_i32_e32 v141, 31, v140
	v_lshlrev_b64 v[148:149], 12, v[140:141]
	v_ashrrev_i32_e32 v139, 31, v138
	v_lshl_add_u64 v[148:149], s[10:11], 0, v[148:149]
	v_lshlrev_b64 v[138:139], 1, v[138:139]
	v_lshl_add_u64 v[154:155], v[148:149], 0, v[138:139]
	global_load_dwordx4 v[160:163], v[154:155], off
	global_load_dwordx4 v[164:167], v[154:155], off offset:256
	v_or_b32_e32 v200, 16, v140
	v_ashrrev_i32_e32 v201, 31, v200
	v_lshlrev_b64 v[202:203], 12, v[200:201]
	v_lshl_add_u64 v[200:201], s[10:11], 0, v[202:203]
	v_lshl_add_u64 v[204:205], v[200:201], 0, v[138:139]
	global_load_dwordx4 v[168:171], v[204:205], off
	v_or_b32_e32 v200, 16, v140
	v_ashrrev_i32_e32 v201, 31, v200
	v_lshlrev_b64 v[202:203], 12, v[200:201]
	v_lshl_add_u64 v[200:201], s[10:11], 0, v[202:203]
	v_lshl_add_u64 v[204:205], v[200:201], 0, v[138:139]
	global_load_dwordx4 v[172:175], v[204:205], off offset:256
	v_or_b32_e32 v200, 32, v140
	v_ashrrev_i32_e32 v201, 31, v200
	v_lshlrev_b64 v[202:203], 12, v[200:201]
	v_lshl_add_u64 v[200:201], s[10:11], 0, v[202:203]
	v_lshl_add_u64 v[204:205], v[200:201], 0, v[138:139]
	global_load_dwordx4 v[176:179], v[204:205], off
	v_or_b32_e32 v200, 32, v140
	v_ashrrev_i32_e32 v201, 31, v200
	v_lshlrev_b64 v[202:203], 12, v[200:201]
	v_lshl_add_u64 v[200:201], s[10:11], 0, v[202:203]
	v_lshl_add_u64 v[204:205], v[200:201], 0, v[138:139]
	global_load_dwordx4 v[180:183], v[204:205], off offset:256
	v_or_b32_e32 v200, 48, v140
	v_ashrrev_i32_e32 v201, 31, v200
	v_lshlrev_b64 v[202:203], 12, v[200:201]
	v_lshl_add_u64 v[200:201], s[10:11], 0, v[202:203]
	v_lshl_add_u64 v[204:205], v[200:201], 0, v[138:139]
	global_load_dwordx4 v[184:187], v[204:205], off
	v_or_b32_e32 v200, 48, v140
	v_ashrrev_i32_e32 v201, 31, v200
	v_lshlrev_b64 v[202:203], 12, v[200:201]
	v_lshl_add_u64 v[200:201], s[10:11], 0, v[202:203]
	v_lshl_add_u64 v[204:205], v[200:201], 0, v[138:139]
	global_load_dwordx4 v[188:191], v[204:205], off offset:256
	v_add_u32_e32 v200, 0x80, v140
	v_ashrrev_i32_e32 v201, 31, v200
	v_lshlrev_b64 v[202:203], 12, v[200:201]
	v_lshl_add_u64 v[200:201], s[10:11], 0, v[202:203]
	v_lshl_add_u64 v[204:205], v[200:201], 0, v[138:139]
	global_load_dwordx4 v[192:195], v[204:205], off
	v_add_u32_e32 v200, 0x80, v140
	v_ashrrev_i32_e32 v201, 31, v200
	v_lshlrev_b64 v[202:203], 12, v[200:201]
	v_lshl_add_u64 v[200:201], s[10:11], 0, v[202:203]
	v_lshl_add_u64 v[204:205], v[200:201], 0, v[138:139]
	global_load_dwordx4 v[196:199], v[204:205], off offset:256
	v_lshlrev_b64 v[152:153], 11, v[140:141]
	s_mov_b64 s[0:1], -1
	s_andn2_b64 vcc, exec, s[6:7]
	s_waitcnt vmcnt(9)
	v_lshlrev_b32_e32 v156, 16, v160
	v_and_b32_e32 v157, 0xffff0000, v160
	v_lshlrev_b32_e32 v148, 16, v161
	v_and_b32_e32 v149, 0xffff0000, v161
	v_pk_mul_f32 v[126:127], v[126:127], v[148:149]
	v_lshlrev_b32_e32 v148, 16, v162
	v_and_b32_e32 v149, 0xffff0000, v162
	v_pk_mul_f32 v[148:149], v[120:121], v[148:149]
	v_lshlrev_b32_e32 v120, 16, v163
	v_and_b32_e32 v121, 0xffff0000, v163
	v_add_u32_e32 v200, 0x90, v140
	v_ashrrev_i32_e32 v201, 31, v200
	v_lshlrev_b64 v[202:203], 12, v[200:201]
	v_lshl_add_u64 v[200:201], s[10:11], 0, v[202:203]
	v_lshl_add_u64 v[204:205], v[200:201], 0, v[138:139]
	global_load_dwordx4 v[160:163], v[204:205], off
	v_pk_mul_f32 v[124:125], v[124:125], v[156:157]
	v_pk_mul_f32 v[150:151], v[122:123], v[120:121]
	v_lshl_add_u64 v[120:121], s[12:13], 0, v[152:153]
	v_lshl_add_u64 v[152:153], v[120:121], 0, v[138:139]
	v_cvt_pk_bf16_f32 v120, v124, v125
	v_cvt_pk_bf16_f32 v121, v126, v127
	v_cvt_pk_bf16_f32 v122, v148, v149
	v_cvt_pk_bf16_f32 v123, v150, v151
	global_store_dwordx4 v[152:153], v[120:123], off
	s_waitcnt vmcnt(0)
	v_lshlrev_b32_e32 v124, 16, v164
	v_and_b32_e32 v125, 0xffff0000, v164
	v_lshlrev_b32_e32 v120, 16, v165
	v_and_b32_e32 v121, 0xffff0000, v165
	v_pk_mul_f32 v[118:119], v[118:119], v[120:121]
	v_lshlrev_b32_e32 v120, 16, v166
	v_and_b32_e32 v121, 0xffff0000, v166
	v_pk_mul_f32 v[120:121], v[112:113], v[120:121]
	v_lshlrev_b32_e32 v112, 16, v167
	v_and_b32_e32 v113, 0xffff0000, v167
	v_add_u32_e32 v200, 0x90, v140
	v_ashrrev_i32_e32 v201, 31, v200
	v_lshlrev_b64 v[202:203], 12, v[200:201]
	v_lshl_add_u64 v[200:201], s[10:11], 0, v[202:203]
	v_lshl_add_u64 v[204:205], v[200:201], 0, v[138:139]
	global_load_dwordx4 v[164:167], v[204:205], off offset:256
	v_pk_mul_f32 v[116:117], v[116:117], v[124:125]
	v_pk_mul_f32 v[122:123], v[114:115], v[112:113]
	v_cvt_pk_bf16_f32 v112, v116, v117
	v_cvt_pk_bf16_f32 v113, v118, v119
	v_cvt_pk_bf16_f32 v114, v120, v121
	v_cvt_pk_bf16_f32 v115, v122, v123
	global_store_dwordx4 v[152:153], v[112:115], off offset:256
	s_nop 1
	v_or_b32_e32 v112, 16, v140
	v_ashrrev_i32_e32 v113, 31, v112
	v_lshlrev_b64 v[114:115], 12, v[112:113]
	v_lshlrev_b64 v[116:117], 11, v[112:113]
	v_lshl_add_u64 v[112:113], s[10:11], 0, v[114:115]
	v_lshl_add_u64 v[118:119], v[112:113], 0, v[138:139]
	s_waitcnt vmcnt(0)
	v_lshlrev_b32_e32 v120, 16, v168
	v_and_b32_e32 v121, 0xffff0000, v168
	v_lshlrev_b32_e32 v112, 16, v169
	v_and_b32_e32 v113, 0xffff0000, v169
	v_pk_mul_f32 v[110:111], v[110:111], v[112:113]
	v_lshlrev_b32_e32 v112, 16, v170
	v_and_b32_e32 v113, 0xffff0000, v170
	v_pk_mul_f32 v[112:113], v[104:105], v[112:113]
	v_lshlrev_b32_e32 v104, 16, v171
	v_and_b32_e32 v105, 0xffff0000, v171
	v_add_u32_e32 v200, 0xa0, v140
	v_ashrrev_i32_e32 v201, 31, v200
	v_lshlrev_b64 v[202:203], 12, v[200:201]
	v_lshl_add_u64 v[200:201], s[10:11], 0, v[202:203]
	v_lshl_add_u64 v[204:205], v[200:201], 0, v[138:139]
	global_load_dwordx4 v[168:171], v[204:205], off
	v_pk_mul_f32 v[108:109], v[108:109], v[120:121]
	v_pk_mul_f32 v[114:115], v[106:107], v[104:105]
	v_lshl_add_u64 v[104:105], s[12:13], 0, v[116:117]
	v_lshl_add_u64 v[116:117], v[104:105], 0, v[138:139]
	v_cvt_pk_bf16_f32 v104, v108, v109
	v_cvt_pk_bf16_f32 v105, v110, v111
	v_cvt_pk_bf16_f32 v106, v112, v113
	v_cvt_pk_bf16_f32 v107, v114, v115
	global_store_dwordx4 v[116:117], v[104:107], off
	s_waitcnt vmcnt(0)
	v_lshlrev_b32_e32 v108, 16, v172
	v_and_b32_e32 v109, 0xffff0000, v172
	v_lshlrev_b32_e32 v104, 16, v173
	v_and_b32_e32 v105, 0xffff0000, v173
	v_pk_mul_f32 v[102:103], v[102:103], v[104:105]
	v_lshlrev_b32_e32 v104, 16, v174
	v_and_b32_e32 v105, 0xffff0000, v174
	v_pk_mul_f32 v[104:105], v[96:97], v[104:105]
	v_lshlrev_b32_e32 v96, 16, v175
	v_and_b32_e32 v97, 0xffff0000, v175
	v_add_u32_e32 v200, 0xa0, v140
	v_ashrrev_i32_e32 v201, 31, v200
	v_lshlrev_b64 v[202:203], 12, v[200:201]
	v_lshl_add_u64 v[200:201], s[10:11], 0, v[202:203]
	v_lshl_add_u64 v[204:205], v[200:201], 0, v[138:139]
	global_load_dwordx4 v[172:175], v[204:205], off offset:256
	v_pk_mul_f32 v[100:101], v[100:101], v[108:109]
	v_pk_mul_f32 v[106:107], v[98:99], v[96:97]
	v_cvt_pk_bf16_f32 v96, v100, v101
	v_cvt_pk_bf16_f32 v97, v102, v103
	v_cvt_pk_bf16_f32 v98, v104, v105
	v_cvt_pk_bf16_f32 v99, v106, v107
	global_store_dwordx4 v[116:117], v[96:99], off offset:256
	s_nop 1
	v_or_b32_e32 v96, 32, v140
	v_ashrrev_i32_e32 v97, 31, v96
	v_lshlrev_b64 v[98:99], 12, v[96:97]
	v_lshlrev_b64 v[100:101], 11, v[96:97]
	v_lshl_add_u64 v[96:97], s[10:11], 0, v[98:99]
	v_lshl_add_u64 v[102:103], v[96:97], 0, v[138:139]
	s_waitcnt vmcnt(0)
	v_lshlrev_b32_e32 v104, 16, v176
	v_and_b32_e32 v105, 0xffff0000, v176
	v_lshlrev_b32_e32 v96, 16, v177
	v_and_b32_e32 v97, 0xffff0000, v177
	v_pk_mul_f32 v[94:95], v[94:95], v[96:97]
	v_lshlrev_b32_e32 v96, 16, v178
	v_and_b32_e32 v97, 0xffff0000, v178
	v_pk_mul_f32 v[96:97], v[88:89], v[96:97]
	v_lshlrev_b32_e32 v88, 16, v179
	v_and_b32_e32 v89, 0xffff0000, v179
	v_add_u32_e32 v200, 0xb0, v140
	v_ashrrev_i32_e32 v201, 31, v200
	v_lshlrev_b64 v[202:203], 12, v[200:201]
	v_lshl_add_u64 v[200:201], s[10:11], 0, v[202:203]
	v_lshl_add_u64 v[204:205], v[200:201], 0, v[138:139]
	global_load_dwordx4 v[176:179], v[204:205], off
	v_pk_mul_f32 v[92:93], v[92:93], v[104:105]
	v_pk_mul_f32 v[98:99], v[90:91], v[88:89]
	v_lshl_add_u64 v[88:89], s[12:13], 0, v[100:101]
	v_lshl_add_u64 v[100:101], v[88:89], 0, v[138:139]
	v_cvt_pk_bf16_f32 v88, v92, v93
	v_cvt_pk_bf16_f32 v89, v94, v95
	v_cvt_pk_bf16_f32 v90, v96, v97
	v_cvt_pk_bf16_f32 v91, v98, v99
	global_store_dwordx4 v[100:101], v[88:91], off
	s_waitcnt vmcnt(0)
	v_lshlrev_b32_e32 v92, 16, v180
	v_and_b32_e32 v93, 0xffff0000, v180
	v_lshlrev_b32_e32 v88, 16, v181
	v_and_b32_e32 v89, 0xffff0000, v181
	v_pk_mul_f32 v[86:87], v[86:87], v[88:89]
	v_lshlrev_b32_e32 v88, 16, v182
	v_and_b32_e32 v89, 0xffff0000, v182
	v_pk_mul_f32 v[88:89], v[80:81], v[88:89]
	v_lshlrev_b32_e32 v80, 16, v183
	v_and_b32_e32 v81, 0xffff0000, v183
	v_add_u32_e32 v200, 0xb0, v140
	v_ashrrev_i32_e32 v201, 31, v200
	v_lshlrev_b64 v[202:203], 12, v[200:201]
	v_lshl_add_u64 v[200:201], s[10:11], 0, v[202:203]
	v_lshl_add_u64 v[204:205], v[200:201], 0, v[138:139]
	global_load_dwordx4 v[180:183], v[204:205], off offset:256
	v_pk_mul_f32 v[84:85], v[84:85], v[92:93]
	v_pk_mul_f32 v[90:91], v[82:83], v[80:81]
	v_cvt_pk_bf16_f32 v80, v84, v85
	v_cvt_pk_bf16_f32 v81, v86, v87
	v_cvt_pk_bf16_f32 v82, v88, v89
	v_cvt_pk_bf16_f32 v83, v90, v91
	global_store_dwordx4 v[100:101], v[80:83], off offset:256
	s_nop 1
	v_or_b32_e32 v80, 48, v140
	v_ashrrev_i32_e32 v81, 31, v80
	v_lshlrev_b64 v[82:83], 12, v[80:81]
	v_lshlrev_b64 v[84:85], 11, v[80:81]
	v_lshl_add_u64 v[80:81], s[10:11], 0, v[82:83]
	v_lshl_add_u64 v[86:87], v[80:81], 0, v[138:139]
	s_waitcnt vmcnt(0)
	v_lshlrev_b32_e32 v88, 16, v184
	v_and_b32_e32 v89, 0xffff0000, v184
	v_lshlrev_b32_e32 v80, 16, v185
	v_and_b32_e32 v81, 0xffff0000, v185
	v_pk_mul_f32 v[78:79], v[78:79], v[80:81]
	v_lshlrev_b32_e32 v80, 16, v186
	v_and_b32_e32 v81, 0xffff0000, v186
	v_pk_mul_f32 v[80:81], v[72:73], v[80:81]
	v_lshlrev_b32_e32 v72, 16, v187
	v_and_b32_e32 v73, 0xffff0000, v187
	v_pk_mul_f32 v[76:77], v[76:77], v[88:89]
	v_pk_mul_f32 v[82:83], v[74:75], v[72:73]
	v_lshl_add_u64 v[72:73], s[12:13], 0, v[84:85]
	v_lshl_add_u64 v[84:85], v[72:73], 0, v[138:139]
	v_cvt_pk_bf16_f32 v72, v76, v77
	v_cvt_pk_bf16_f32 v73, v78, v79
	v_cvt_pk_bf16_f32 v74, v80, v81
	v_cvt_pk_bf16_f32 v75, v82, v83
	global_store_dwordx4 v[84:85], v[72:75], off
	s_waitcnt vmcnt(0)
	v_lshlrev_b32_e32 v76, 16, v188
	v_and_b32_e32 v77, 0xffff0000, v188
	v_lshlrev_b32_e32 v72, 16, v189
	v_and_b32_e32 v73, 0xffff0000, v189
	v_pk_mul_f32 v[70:71], v[70:71], v[72:73]
	v_lshlrev_b32_e32 v72, 16, v190
	v_and_b32_e32 v73, 0xffff0000, v190
	v_pk_mul_f32 v[72:73], v[64:65], v[72:73]
	v_lshlrev_b32_e32 v64, 16, v191
	v_and_b32_e32 v65, 0xffff0000, v191
	v_pk_mul_f32 v[68:69], v[68:69], v[76:77]
	v_pk_mul_f32 v[74:75], v[66:67], v[64:65]
	v_cvt_pk_bf16_f32 v64, v68, v69
	v_cvt_pk_bf16_f32 v65, v70, v71
	v_cvt_pk_bf16_f32 v66, v72, v73
	v_cvt_pk_bf16_f32 v67, v74, v75
	global_store_dwordx4 v[84:85], v[64:67], off offset:256
	s_nop 1
	v_add_u32_e32 v64, 0x80, v140
	v_ashrrev_i32_e32 v65, 31, v64
	v_lshlrev_b64 v[66:67], 12, v[64:65]
	v_lshlrev_b64 v[68:69], 11, v[64:65]
	v_lshl_add_u64 v[64:65], s[10:11], 0, v[66:67]
	v_lshl_add_u64 v[70:71], v[64:65], 0, v[138:139]
	s_waitcnt vmcnt(0)
	v_lshlrev_b32_e32 v72, 16, v192
	v_and_b32_e32 v73, 0xffff0000, v192
	v_lshlrev_b32_e32 v64, 16, v193
	v_and_b32_e32 v65, 0xffff0000, v193
	v_pk_mul_f32 v[62:63], v[62:63], v[64:65]
	v_lshlrev_b32_e32 v64, 16, v194
	v_and_b32_e32 v65, 0xffff0000, v194
	v_pk_mul_f32 v[64:65], v[56:57], v[64:65]
	v_lshlrev_b32_e32 v56, 16, v195
	v_and_b32_e32 v57, 0xffff0000, v195
	v_pk_mul_f32 v[60:61], v[60:61], v[72:73]
	v_pk_mul_f32 v[66:67], v[58:59], v[56:57]
	v_lshl_add_u64 v[56:57], s[12:13], 0, v[68:69]
	v_lshl_add_u64 v[68:69], v[56:57], 0, v[138:139]
	v_cvt_pk_bf16_f32 v56, v60, v61
	v_cvt_pk_bf16_f32 v57, v62, v63
	v_cvt_pk_bf16_f32 v58, v64, v65
	v_cvt_pk_bf16_f32 v59, v66, v67
	global_store_dwordx4 v[68:69], v[56:59], off
	s_waitcnt vmcnt(0)
	v_lshlrev_b32_e32 v60, 16, v196
	v_and_b32_e32 v61, 0xffff0000, v196
	v_lshlrev_b32_e32 v56, 16, v197
	v_and_b32_e32 v57, 0xffff0000, v197
	v_pk_mul_f32 v[54:55], v[54:55], v[56:57]
	v_lshlrev_b32_e32 v56, 16, v198
	v_and_b32_e32 v57, 0xffff0000, v198
	v_pk_mul_f32 v[56:57], v[48:49], v[56:57]
	v_lshlrev_b32_e32 v48, 16, v199
	v_and_b32_e32 v49, 0xffff0000, v199
	v_pk_mul_f32 v[52:53], v[52:53], v[60:61]
	v_pk_mul_f32 v[58:59], v[50:51], v[48:49]
	v_cvt_pk_bf16_f32 v48, v52, v53
	v_cvt_pk_bf16_f32 v49, v54, v55
	v_cvt_pk_bf16_f32 v50, v56, v57
	v_cvt_pk_bf16_f32 v51, v58, v59
	global_store_dwordx4 v[68:69], v[48:51], off offset:256
	s_nop 1
	v_add_u32_e32 v48, 0x90, v140
	v_ashrrev_i32_e32 v49, 31, v48
	v_lshlrev_b64 v[50:51], 12, v[48:49]
	v_lshlrev_b64 v[52:53], 11, v[48:49]
	v_lshl_add_u64 v[48:49], s[10:11], 0, v[50:51]
	v_lshl_add_u64 v[54:55], v[48:49], 0, v[138:139]
	s_waitcnt vmcnt(0)
	v_lshlrev_b32_e32 v56, 16, v160
	v_and_b32_e32 v57, 0xffff0000, v160
	v_lshlrev_b32_e32 v48, 16, v161
	v_and_b32_e32 v49, 0xffff0000, v161
	v_pk_mul_f32 v[46:47], v[46:47], v[48:49]
	v_lshlrev_b32_e32 v48, 16, v162
	v_and_b32_e32 v49, 0xffff0000, v162
	v_pk_mul_f32 v[48:49], v[40:41], v[48:49]
	v_lshlrev_b32_e32 v40, 16, v163
	v_and_b32_e32 v41, 0xffff0000, v163
	v_pk_mul_f32 v[44:45], v[44:45], v[56:57]
	v_pk_mul_f32 v[50:51], v[42:43], v[40:41]
	v_lshl_add_u64 v[40:41], s[12:13], 0, v[52:53]
	v_lshl_add_u64 v[52:53], v[40:41], 0, v[138:139]
	v_cvt_pk_bf16_f32 v40, v44, v45
	v_cvt_pk_bf16_f32 v41, v46, v47
	v_cvt_pk_bf16_f32 v42, v48, v49
	v_cvt_pk_bf16_f32 v43, v50, v51
	global_store_dwordx4 v[52:53], v[40:43], off
	s_waitcnt vmcnt(0)
	v_lshlrev_b32_e32 v44, 16, v164
	v_and_b32_e32 v45, 0xffff0000, v164
	v_lshlrev_b32_e32 v40, 16, v165
	v_and_b32_e32 v41, 0xffff0000, v165
	v_pk_mul_f32 v[38:39], v[38:39], v[40:41]
	v_lshlrev_b32_e32 v40, 16, v166
	v_and_b32_e32 v41, 0xffff0000, v166
	v_pk_mul_f32 v[40:41], v[32:33], v[40:41]
	v_lshlrev_b32_e32 v32, 16, v167
	v_and_b32_e32 v33, 0xffff0000, v167
	v_pk_mul_f32 v[36:37], v[36:37], v[44:45]
	v_pk_mul_f32 v[42:43], v[34:35], v[32:33]
	v_cvt_pk_bf16_f32 v32, v36, v37
	v_cvt_pk_bf16_f32 v33, v38, v39
	v_cvt_pk_bf16_f32 v34, v40, v41
	v_cvt_pk_bf16_f32 v35, v42, v43
	global_store_dwordx4 v[52:53], v[32:35], off offset:256
	s_nop 1
	v_add_u32_e32 v32, 0xa0, v140
	v_ashrrev_i32_e32 v33, 31, v32
	v_lshlrev_b64 v[34:35], 12, v[32:33]
	v_lshlrev_b64 v[36:37], 11, v[32:33]
	v_lshl_add_u64 v[32:33], s[10:11], 0, v[34:35]
	v_lshl_add_u64 v[38:39], v[32:33], 0, v[138:139]
	s_waitcnt vmcnt(0)
	v_lshlrev_b32_e32 v40, 16, v168
	v_and_b32_e32 v41, 0xffff0000, v168
	v_lshlrev_b32_e32 v32, 16, v169
	v_and_b32_e32 v33, 0xffff0000, v169
	v_pk_mul_f32 v[30:31], v[30:31], v[32:33]
	v_lshlrev_b32_e32 v32, 16, v170
	v_and_b32_e32 v33, 0xffff0000, v170
	v_pk_mul_f32 v[32:33], v[24:25], v[32:33]
	v_lshlrev_b32_e32 v24, 16, v171
	v_and_b32_e32 v25, 0xffff0000, v171
	v_pk_mul_f32 v[28:29], v[28:29], v[40:41]
	v_pk_mul_f32 v[34:35], v[26:27], v[24:25]
	v_lshl_add_u64 v[24:25], s[12:13], 0, v[36:37]
	v_lshl_add_u64 v[36:37], v[24:25], 0, v[138:139]
	v_cvt_pk_bf16_f32 v24, v28, v29
	v_cvt_pk_bf16_f32 v25, v30, v31
	v_cvt_pk_bf16_f32 v26, v32, v33
	v_cvt_pk_bf16_f32 v27, v34, v35
	global_store_dwordx4 v[36:37], v[24:27], off
	s_waitcnt vmcnt(0)
	v_lshlrev_b32_e32 v28, 16, v172
	v_and_b32_e32 v29, 0xffff0000, v172
	v_lshlrev_b32_e32 v24, 16, v173
	v_and_b32_e32 v25, 0xffff0000, v173
	v_pk_mul_f32 v[22:23], v[22:23], v[24:25]
	v_lshlrev_b32_e32 v24, 16, v174
	v_and_b32_e32 v25, 0xffff0000, v174
	v_pk_mul_f32 v[24:25], v[16:17], v[24:25]
	v_lshlrev_b32_e32 v16, 16, v175
	v_and_b32_e32 v17, 0xffff0000, v175
	v_pk_mul_f32 v[20:21], v[20:21], v[28:29]
	v_pk_mul_f32 v[26:27], v[18:19], v[16:17]
	v_cvt_pk_bf16_f32 v16, v20, v21
	v_cvt_pk_bf16_f32 v17, v22, v23
	v_cvt_pk_bf16_f32 v18, v24, v25
	v_cvt_pk_bf16_f32 v19, v26, v27
	global_store_dwordx4 v[36:37], v[16:19], off offset:256
	s_nop 1
	v_add_u32_e32 v16, 0xb0, v140
	v_ashrrev_i32_e32 v17, 31, v16
	v_lshlrev_b64 v[18:19], 12, v[16:17]
	v_lshlrev_b64 v[20:21], 11, v[16:17]
	v_lshl_add_u64 v[16:17], s[10:11], 0, v[18:19]
	v_lshl_add_u64 v[22:23], v[16:17], 0, v[138:139]
	s_waitcnt vmcnt(0)
	v_lshlrev_b32_e32 v24, 16, v176
	v_and_b32_e32 v25, 0xffff0000, v176
	v_lshlrev_b32_e32 v16, 16, v177
	v_and_b32_e32 v17, 0xffff0000, v177
	v_pk_mul_f32 v[14:15], v[14:15], v[16:17]
	v_lshlrev_b32_e32 v16, 16, v178
	v_and_b32_e32 v17, 0xffff0000, v178
	v_pk_mul_f32 v[16:17], v[8:9], v[16:17]
	v_lshlrev_b32_e32 v8, 16, v179
	v_and_b32_e32 v9, 0xffff0000, v179
	v_pk_mul_f32 v[12:13], v[12:13], v[24:25]
	v_pk_mul_f32 v[18:19], v[10:11], v[8:9]
	v_lshl_add_u64 v[8:9], s[12:13], 0, v[20:21]
	v_lshl_add_u64 v[20:21], v[8:9], 0, v[138:139]
	v_cvt_pk_bf16_f32 v8, v12, v13
	v_cvt_pk_bf16_f32 v9, v14, v15
	v_cvt_pk_bf16_f32 v10, v16, v17
	v_cvt_pk_bf16_f32 v11, v18, v19
	global_store_dwordx4 v[20:21], v[8:11], off
	s_waitcnt vmcnt(0)
	v_lshlrev_b32_e32 v12, 16, v180
	v_and_b32_e32 v13, 0xffff0000, v180
	v_lshlrev_b32_e32 v8, 16, v181
	v_and_b32_e32 v9, 0xffff0000, v181
	v_pk_mul_f32 v[6:7], v[6:7], v[8:9]
	v_lshlrev_b32_e32 v8, 16, v182
	v_and_b32_e32 v9, 0xffff0000, v182
	v_pk_mul_f32 v[8:9], v[0:1], v[8:9]
	v_lshlrev_b32_e32 v0, 16, v183
	v_and_b32_e32 v1, 0xffff0000, v183
	v_pk_mul_f32 v[4:5], v[4:5], v[12:13]
	v_pk_mul_f32 v[10:11], v[2:3], v[0:1]
	v_cvt_pk_bf16_f32 v0, v4, v5
	v_cvt_pk_bf16_f32 v1, v6, v7
	v_cvt_pk_bf16_f32 v2, v8, v9
	v_cvt_pk_bf16_f32 v3, v10, v11
	global_store_dwordx4 v[20:21], v[0:3], off offset:256
	s_cbranch_vccnz .LBB0_1301
	s_andn2_b64 vcc, exec, s[14:15]
	s_cbranch_vccnz .LBB0_1300
	s_barrier
	s_branch .LBB0_1300

.LBB0_1332:
	v_lshl_add_u32 v140, s5, 8, v143
	v_lshl_or_b32 v138, s4, 8, v145
	v_ashrrev_i32_e32 v141, 31, v140
	v_lshlrev_b64 v[148:149], 12, v[140:141]
	v_lshlrev_b64 v[152:153], 11, v[140:141]
	v_ashrrev_i32_e32 v139, 31, v138
	v_lshl_add_u64 v[148:149], s[10:11], 0, v[148:149]
	v_lshlrev_b64 v[138:139], 1, v[138:139]
	v_lshl_add_u64 v[152:153], s[12:13], 0, v[152:153]
	v_lshl_add_u64 v[156:157], v[148:149], 0, v[138:139]
	v_lshl_add_u64 v[158:159], v[152:153], 0, v[138:139]
	global_load_dwordx4 v[164:167], v[156:157], off offset:2048
	global_load_dwordx4 v[168:171], v[158:159], off
	global_load_dwordx4 v[172:175], v[156:157], off offset:2304
	global_load_dwordx4 v[176:179], v[158:159], off offset:256
	v_or_b32_e32 v200, 16, v140
	v_ashrrev_i32_e32 v201, 31, v200
	v_lshlrev_b64 v[202:203], 12, v[200:201]
	v_lshl_add_u64 v[200:201], s[10:11], 0, v[202:203]
	v_lshl_add_u64 v[204:205], v[200:201], 0, v[138:139]
	global_load_dwordx4 v[180:183], v[204:205], off offset:2048
	s_mov_b64 s[0:1], -1
	s_andn2_b64 vcc, exec, s[6:7]
	s_waitcnt vmcnt(3)
	v_lshlrev_b32_e32 v160, 16, v164
	v_and_b32_e32 v161, 0xffff0000, v164
	v_lshlrev_b32_e32 v162, 16, v168
	v_and_b32_e32 v163, 0xffff0000, v168
	v_lshlrev_b32_e32 v148, 16, v165
	v_and_b32_e32 v149, 0xffff0000, v165
	v_lshlrev_b32_e32 v152, 16, v169
	v_and_b32_e32 v153, 0xffff0000, v169
	v_pk_fma_f32 v[126:127], v[126:127], v[148:149], v[152:153]
	v_lshlrev_b32_e32 v148, 16, v166
	v_and_b32_e32 v149, 0xffff0000, v166
	v_lshlrev_b32_e32 v152, 16, v170
	v_and_b32_e32 v153, 0xffff0000, v170
	v_pk_fma_f32 v[148:149], v[120:121], v[148:149], v[152:153]
	v_lshlrev_b32_e32 v120, 16, v167
	v_and_b32_e32 v121, 0xffff0000, v167
	v_lshlrev_b32_e32 v150, 16, v171
	v_and_b32_e32 v151, 0xffff0000, v171
	v_pk_fma_f32 v[124:125], v[124:125], v[160:161], v[162:163]
	v_pk_fma_f32 v[150:151], v[122:123], v[120:121], v[150:151]
	v_cvt_pk_bf16_f32 v120, v124, v125
	v_cvt_pk_bf16_f32 v121, v126, v127
	v_cvt_pk_bf16_f32 v122, v148, v149
	v_cvt_pk_bf16_f32 v123, v150, v151
	global_store_dwordx4 v[158:159], v[120:123], off
	s_nop 0
	s_waitcnt vmcnt(0)
	v_lshlrev_b32_e32 v148, 16, v172
	v_and_b32_e32 v149, 0xffff0000, v172
	s_waitcnt vmcnt(0)
	v_lshlrev_b32_e32 v150, 16, v176
	v_and_b32_e32 v151, 0xffff0000, v176
	v_lshlrev_b32_e32 v120, 16, v173
	v_and_b32_e32 v121, 0xffff0000, v173
	v_lshlrev_b32_e32 v124, 16, v177
	v_and_b32_e32 v125, 0xffff0000, v177
	v_pk_fma_f32 v[118:119], v[118:119], v[120:121], v[124:125]
	v_lshlrev_b32_e32 v120, 16, v174
	v_and_b32_e32 v121, 0xffff0000, v174
	v_lshlrev_b32_e32 v124, 16, v178
	v_and_b32_e32 v125, 0xffff0000, v178
	v_pk_fma_f32 v[120:121], v[112:113], v[120:121], v[124:125]
	v_lshlrev_b32_e32 v112, 16, v175
	v_and_b32_e32 v113, 0xffff0000, v175
	v_lshlrev_b32_e32 v122, 16, v179
	v_and_b32_e32 v123, 0xffff0000, v179
	v_pk_fma_f32 v[116:117], v[116:117], v[148:149], v[150:151]
	v_pk_fma_f32 v[122:123], v[114:115], v[112:113], v[122:123]
	v_cvt_pk_bf16_f32 v112, v116, v117
	v_cvt_pk_bf16_f32 v113, v118, v119
	v_cvt_pk_bf16_f32 v114, v120, v121
	v_cvt_pk_bf16_f32 v115, v122, v123
	global_store_dwordx4 v[158:159], v[112:115], off offset:256
	s_nop 1
	v_or_b32_e32 v112, 16, v140
	v_ashrrev_i32_e32 v113, 31, v112
	v_lshlrev_b64 v[114:115], 12, v[112:113]
	v_lshlrev_b64 v[116:117], 11, v[112:113]
	v_lshl_add_u64 v[112:113], s[10:11], 0, v[114:115]
	v_lshl_add_u64 v[116:117], s[12:13], 0, v[116:117]
	v_lshl_add_u64 v[120:121], v[112:113], 0, v[138:139]
	v_lshl_add_u64 v[122:123], v[116:117], 0, v[138:139]
	global_load_dwordx4 v[184:187], v[122:123], off
	global_load_dwordx4 v[188:191], v[120:121], off offset:2304
	global_load_dwordx4 v[192:195], v[122:123], off offset:256
	v_or_b32_e32 v200, 32, v140
	v_ashrrev_i32_e32 v201, 31, v200
	v_lshlrev_b64 v[202:203], 12, v[200:201]
	v_lshl_add_u64 v[200:201], s[10:11], 0, v[202:203]
	v_lshl_add_u64 v[204:205], v[200:201], 0, v[138:139]
	global_load_dwordx4 v[196:199], v[204:205], off offset:2048
	s_waitcnt vmcnt(4)
	v_lshlrev_b32_e32 v124, 16, v180
	v_and_b32_e32 v125, 0xffff0000, v180
	s_waitcnt vmcnt(3)
	v_lshlrev_b32_e32 v126, 16, v184
	v_and_b32_e32 v127, 0xffff0000, v184
	v_lshlrev_b32_e32 v112, 16, v181
	v_and_b32_e32 v113, 0xffff0000, v181
	v_lshlrev_b32_e32 v116, 16, v185
	v_and_b32_e32 v117, 0xffff0000, v185
	v_pk_fma_f32 v[110:111], v[110:111], v[112:113], v[116:117]
	v_lshlrev_b32_e32 v112, 16, v182
	v_and_b32_e32 v113, 0xffff0000, v182
	v_lshlrev_b32_e32 v116, 16, v186
	v_and_b32_e32 v117, 0xffff0000, v186
	v_pk_fma_f32 v[112:113], v[104:105], v[112:113], v[116:117]
	v_lshlrev_b32_e32 v104, 16, v183
	v_and_b32_e32 v105, 0xffff0000, v183
	v_lshlrev_b32_e32 v114, 16, v187
	v_and_b32_e32 v115, 0xffff0000, v187
	v_pk_fma_f32 v[108:109], v[108:109], v[124:125], v[126:127]
	v_pk_fma_f32 v[114:115], v[106:107], v[104:105], v[114:115]
	v_cvt_pk_bf16_f32 v104, v108, v109
	v_cvt_pk_bf16_f32 v105, v110, v111
	v_cvt_pk_bf16_f32 v106, v112, v113
	v_cvt_pk_bf16_f32 v107, v114, v115
	global_store_dwordx4 v[122:123], v[104:107], off
	s_nop 0
	s_waitcnt vmcnt(0)
	v_lshlrev_b32_e32 v112, 16, v188
	v_and_b32_e32 v113, 0xffff0000, v188
	s_waitcnt vmcnt(0)
	v_lshlrev_b32_e32 v114, 16, v192
	v_and_b32_e32 v115, 0xffff0000, v192
	v_lshlrev_b32_e32 v104, 16, v189
	v_and_b32_e32 v105, 0xffff0000, v189
	v_lshlrev_b32_e32 v108, 16, v193
	v_and_b32_e32 v109, 0xffff0000, v193
	v_pk_fma_f32 v[102:103], v[102:103], v[104:105], v[108:109]
	v_lshlrev_b32_e32 v104, 16, v190
	v_and_b32_e32 v105, 0xffff0000, v190
	v_lshlrev_b32_e32 v108, 16, v194
	v_and_b32_e32 v109, 0xffff0000, v194
	v_pk_fma_f32 v[104:105], v[96:97], v[104:105], v[108:109]
	v_lshlrev_b32_e32 v96, 16, v191
	v_and_b32_e32 v97, 0xffff0000, v191
	v_lshlrev_b32_e32 v106, 16, v195
	v_and_b32_e32 v107, 0xffff0000, v195
	v_pk_fma_f32 v[100:101], v[100:101], v[112:113], v[114:115]
	v_pk_fma_f32 v[106:107], v[98:99], v[96:97], v[106:107]
	v_cvt_pk_bf16_f32 v96, v100, v101
	v_cvt_pk_bf16_f32 v97, v102, v103
	v_cvt_pk_bf16_f32 v98, v104, v105
	v_cvt_pk_bf16_f32 v99, v106, v107
	global_store_dwordx4 v[122:123], v[96:99], off offset:256
	s_nop 1
	v_or_b32_e32 v96, 32, v140
	v_ashrrev_i32_e32 v97, 31, v96
	v_lshlrev_b64 v[98:99], 12, v[96:97]
	v_lshlrev_b64 v[100:101], 11, v[96:97]
	v_lshl_add_u64 v[96:97], s[10:11], 0, v[98:99]
	v_lshl_add_u64 v[100:101], s[12:13], 0, v[100:101]
	v_lshl_add_u64 v[104:105], v[96:97], 0, v[138:139]
	v_lshl_add_u64 v[106:107], v[100:101], 0, v[138:139]
	global_load_dwordx4 v[164:167], v[106:107], off
	global_load_dwordx4 v[168:171], v[104:105], off offset:2304
	global_load_dwordx4 v[172:175], v[106:107], off offset:256
	v_or_b32_e32 v200, 48, v140
	v_ashrrev_i32_e32 v201, 31, v200
	v_lshlrev_b64 v[202:203], 12, v[200:201]
	v_lshl_add_u64 v[200:201], s[10:11], 0, v[202:203]
	v_lshl_add_u64 v[204:205], v[200:201], 0, v[138:139]
	global_load_dwordx4 v[176:179], v[204:205], off offset:2048
	s_waitcnt vmcnt(4)
	v_lshlrev_b32_e32 v108, 16, v196
	v_and_b32_e32 v109, 0xffff0000, v196
	s_waitcnt vmcnt(3)
	v_lshlrev_b32_e32 v110, 16, v164
	v_and_b32_e32 v111, 0xffff0000, v164
	v_lshlrev_b32_e32 v96, 16, v197
	v_and_b32_e32 v97, 0xffff0000, v197
	v_lshlrev_b32_e32 v100, 16, v165
	v_and_b32_e32 v101, 0xffff0000, v165
	v_pk_fma_f32 v[94:95], v[94:95], v[96:97], v[100:101]
	v_lshlrev_b32_e32 v96, 16, v198
	v_and_b32_e32 v97, 0xffff0000, v198
	v_lshlrev_b32_e32 v100, 16, v166
	v_and_b32_e32 v101, 0xffff0000, v166
	v_pk_fma_f32 v[96:97], v[88:89], v[96:97], v[100:101]
	v_lshlrev_b32_e32 v88, 16, v199
	v_and_b32_e32 v89, 0xffff0000, v199
	v_lshlrev_b32_e32 v98, 16, v167
	v_and_b32_e32 v99, 0xffff0000, v167
	v_pk_fma_f32 v[92:93], v[92:93], v[108:109], v[110:111]
	v_pk_fma_f32 v[98:99], v[90:91], v[88:89], v[98:99]
	v_cvt_pk_bf16_f32 v88, v92, v93
	v_cvt_pk_bf16_f32 v89, v94, v95
	v_cvt_pk_bf16_f32 v90, v96, v97
	v_cvt_pk_bf16_f32 v91, v98, v99
	global_store_dwordx4 v[106:107], v[88:91], off
	s_nop 0
	s_waitcnt vmcnt(0)
	v_lshlrev_b32_e32 v96, 16, v168
	v_and_b32_e32 v97, 0xffff0000, v168
	s_waitcnt vmcnt(0)
	v_lshlrev_b32_e32 v98, 16, v172
	v_and_b32_e32 v99, 0xffff0000, v172
	v_lshlrev_b32_e32 v88, 16, v169
	v_and_b32_e32 v89, 0xffff0000, v169
	v_lshlrev_b32_e32 v92, 16, v173
	v_and_b32_e32 v93, 0xffff0000, v173
	v_pk_fma_f32 v[86:87], v[86:87], v[88:89], v[92:93]
	v_lshlrev_b32_e32 v88, 16, v170
	v_and_b32_e32 v89, 0xffff0000, v170
	v_lshlrev_b32_e32 v92, 16, v174
	v_and_b32_e32 v93, 0xffff0000, v174
	v_pk_fma_f32 v[88:89], v[80:81], v[88:89], v[92:93]
	v_lshlrev_b32_e32 v80, 16, v171
	v_and_b32_e32 v81, 0xffff0000, v171
	v_lshlrev_b32_e32 v90, 16, v175
	v_and_b32_e32 v91, 0xffff0000, v175
	v_pk_fma_f32 v[84:85], v[84:85], v[96:97], v[98:99]
	v_pk_fma_f32 v[90:91], v[82:83], v[80:81], v[90:91]
	v_cvt_pk_bf16_f32 v80, v84, v85
	v_cvt_pk_bf16_f32 v81, v86, v87
	v_cvt_pk_bf16_f32 v82, v88, v89
	v_cvt_pk_bf16_f32 v83, v90, v91
	global_store_dwordx4 v[106:107], v[80:83], off offset:256
	s_nop 1
	v_or_b32_e32 v80, 48, v140
	v_ashrrev_i32_e32 v81, 31, v80
	v_lshlrev_b64 v[82:83], 12, v[80:81]
	v_lshlrev_b64 v[84:85], 11, v[80:81]
	v_lshl_add_u64 v[80:81], s[10:11], 0, v[82:83]
	v_lshl_add_u64 v[84:85], s[12:13], 0, v[84:85]
	v_lshl_add_u64 v[88:89], v[80:81], 0, v[138:139]
	v_lshl_add_u64 v[90:91], v[84:85], 0, v[138:139]
	global_load_dwordx4 v[180:183], v[90:91], off
	global_load_dwordx4 v[184:187], v[88:89], off offset:2304
	global_load_dwordx4 v[188:191], v[90:91], off offset:256
	v_add_u32_e32 v200, 0x80, v140
	v_ashrrev_i32_e32 v201, 31, v200
	v_lshlrev_b64 v[202:203], 12, v[200:201]
	v_lshl_add_u64 v[200:201], s[10:11], 0, v[202:203]
	v_lshl_add_u64 v[204:205], v[200:201], 0, v[138:139]
	global_load_dwordx4 v[192:195], v[204:205], off offset:2048
	s_waitcnt vmcnt(4)
	v_lshlrev_b32_e32 v92, 16, v176
	v_and_b32_e32 v93, 0xffff0000, v176
	s_waitcnt vmcnt(3)
	v_lshlrev_b32_e32 v94, 16, v180
	v_and_b32_e32 v95, 0xffff0000, v180
	v_lshlrev_b32_e32 v80, 16, v177
	v_and_b32_e32 v81, 0xffff0000, v177
	v_lshlrev_b32_e32 v84, 16, v181
	v_and_b32_e32 v85, 0xffff0000, v181
	v_pk_fma_f32 v[78:79], v[78:79], v[80:81], v[84:85]
	v_lshlrev_b32_e32 v80, 16, v178
	v_and_b32_e32 v81, 0xffff0000, v178
	v_lshlrev_b32_e32 v84, 16, v182
	v_and_b32_e32 v85, 0xffff0000, v182
	v_pk_fma_f32 v[80:81], v[72:73], v[80:81], v[84:85]
	v_lshlrev_b32_e32 v72, 16, v179
	v_and_b32_e32 v73, 0xffff0000, v179
	v_lshlrev_b32_e32 v82, 16, v183
	v_and_b32_e32 v83, 0xffff0000, v183
	v_pk_fma_f32 v[76:77], v[76:77], v[92:93], v[94:95]
	v_pk_fma_f32 v[82:83], v[74:75], v[72:73], v[82:83]
	v_cvt_pk_bf16_f32 v72, v76, v77
	v_cvt_pk_bf16_f32 v73, v78, v79
	v_cvt_pk_bf16_f32 v74, v80, v81
	v_cvt_pk_bf16_f32 v75, v82, v83
	global_store_dwordx4 v[90:91], v[72:75], off
	s_nop 0
	s_waitcnt vmcnt(0)
	v_lshlrev_b32_e32 v80, 16, v184
	v_and_b32_e32 v81, 0xffff0000, v184
	s_waitcnt vmcnt(0)
	v_lshlrev_b32_e32 v82, 16, v188
	v_and_b32_e32 v83, 0xffff0000, v188
	v_lshlrev_b32_e32 v72, 16, v185
	v_and_b32_e32 v73, 0xffff0000, v185
	v_lshlrev_b32_e32 v76, 16, v189
	v_and_b32_e32 v77, 0xffff0000, v189
	v_pk_fma_f32 v[70:71], v[70:71], v[72:73], v[76:77]
	v_lshlrev_b32_e32 v72, 16, v186
	v_and_b32_e32 v73, 0xffff0000, v186
	v_lshlrev_b32_e32 v76, 16, v190
	v_and_b32_e32 v77, 0xffff0000, v190
	v_pk_fma_f32 v[72:73], v[64:65], v[72:73], v[76:77]
	v_lshlrev_b32_e32 v64, 16, v187
	v_and_b32_e32 v65, 0xffff0000, v187
	v_lshlrev_b32_e32 v74, 16, v191
	v_and_b32_e32 v75, 0xffff0000, v191
	v_pk_fma_f32 v[68:69], v[68:69], v[80:81], v[82:83]
	v_pk_fma_f32 v[74:75], v[66:67], v[64:65], v[74:75]
	v_cvt_pk_bf16_f32 v64, v68, v69
	v_cvt_pk_bf16_f32 v65, v70, v71
	v_cvt_pk_bf16_f32 v66, v72, v73
	v_cvt_pk_bf16_f32 v67, v74, v75
	global_store_dwordx4 v[90:91], v[64:67], off offset:256
	s_nop 1
	v_add_u32_e32 v64, 0x80, v140
	v_ashrrev_i32_e32 v65, 31, v64
	v_lshlrev_b64 v[66:67], 12, v[64:65]
	v_lshlrev_b64 v[68:69], 11, v[64:65]
	v_lshl_add_u64 v[64:65], s[10:11], 0, v[66:67]
	v_lshl_add_u64 v[68:69], s[12:13], 0, v[68:69]
	v_lshl_add_u64 v[72:73], v[64:65], 0, v[138:139]
	v_lshl_add_u64 v[74:75], v[68:69], 0, v[138:139]
	global_load_dwordx4 v[196:199], v[74:75], off
	global_load_dwordx4 v[164:167], v[72:73], off offset:2304
	global_load_dwordx4 v[168:171], v[74:75], off offset:256
	v_add_u32_e32 v200, 0x90, v140
	v_ashrrev_i32_e32 v201, 31, v200
	v_lshlrev_b64 v[202:203], 12, v[200:201]
	v_lshl_add_u64 v[200:201], s[10:11], 0, v[202:203]
	v_lshl_add_u64 v[204:205], v[200:201], 0, v[138:139]
	global_load_dwordx4 v[172:175], v[204:205], off offset:2048
	s_waitcnt vmcnt(4)
	v_lshlrev_b32_e32 v76, 16, v192
	v_and_b32_e32 v77, 0xffff0000, v192
	s_waitcnt vmcnt(3)
	v_lshlrev_b32_e32 v78, 16, v196
	v_and_b32_e32 v79, 0xffff0000, v196
	v_lshlrev_b32_e32 v64, 16, v193
	v_and_b32_e32 v65, 0xffff0000, v193
	v_lshlrev_b32_e32 v68, 16, v197
	v_and_b32_e32 v69, 0xffff0000, v197
	v_pk_fma_f32 v[62:63], v[62:63], v[64:65], v[68:69]
	v_lshlrev_b32_e32 v64, 16, v194
	v_and_b32_e32 v65, 0xffff0000, v194
	v_lshlrev_b32_e32 v68, 16, v198
	v_and_b32_e32 v69, 0xffff0000, v198
	v_pk_fma_f32 v[64:65], v[56:57], v[64:65], v[68:69]
	v_lshlrev_b32_e32 v56, 16, v195
	v_and_b32_e32 v57, 0xffff0000, v195
	v_lshlrev_b32_e32 v66, 16, v199
	v_and_b32_e32 v67, 0xffff0000, v199
	v_pk_fma_f32 v[60:61], v[60:61], v[76:77], v[78:79]
	v_pk_fma_f32 v[66:67], v[58:59], v[56:57], v[66:67]
	v_cvt_pk_bf16_f32 v56, v60, v61
	v_cvt_pk_bf16_f32 v57, v62, v63
	v_cvt_pk_bf16_f32 v58, v64, v65
	v_cvt_pk_bf16_f32 v59, v66, v67
	global_store_dwordx4 v[74:75], v[56:59], off
	s_nop 0
	s_waitcnt vmcnt(0)
	v_lshlrev_b32_e32 v64, 16, v164
	v_and_b32_e32 v65, 0xffff0000, v164
	s_waitcnt vmcnt(0)
	v_lshlrev_b32_e32 v66, 16, v168
	v_and_b32_e32 v67, 0xffff0000, v168
	v_lshlrev_b32_e32 v56, 16, v165
	v_and_b32_e32 v57, 0xffff0000, v165
	v_lshlrev_b32_e32 v60, 16, v169
	v_and_b32_e32 v61, 0xffff0000, v169
	v_pk_fma_f32 v[54:55], v[54:55], v[56:57], v[60:61]
	v_lshlrev_b32_e32 v56, 16, v166
	v_and_b32_e32 v57, 0xffff0000, v166
	v_lshlrev_b32_e32 v60, 16, v170
	v_and_b32_e32 v61, 0xffff0000, v170
	v_pk_fma_f32 v[56:57], v[48:49], v[56:57], v[60:61]
	v_lshlrev_b32_e32 v48, 16, v167
	v_and_b32_e32 v49, 0xffff0000, v167
	v_lshlrev_b32_e32 v58, 16, v171
	v_and_b32_e32 v59, 0xffff0000, v171
	v_pk_fma_f32 v[52:53], v[52:53], v[64:65], v[66:67]
	v_pk_fma_f32 v[58:59], v[50:51], v[48:49], v[58:59]
	v_cvt_pk_bf16_f32 v48, v52, v53
	v_cvt_pk_bf16_f32 v49, v54, v55
	v_cvt_pk_bf16_f32 v50, v56, v57
	v_cvt_pk_bf16_f32 v51, v58, v59
	global_store_dwordx4 v[74:75], v[48:51], off offset:256
	s_nop 1
	v_add_u32_e32 v48, 0x90, v140
	v_ashrrev_i32_e32 v49, 31, v48
	v_lshlrev_b64 v[50:51], 12, v[48:49]
	v_lshlrev_b64 v[52:53], 11, v[48:49]
	v_lshl_add_u64 v[48:49], s[10:11], 0, v[50:51]
	v_lshl_add_u64 v[52:53], s[12:13], 0, v[52:53]
	v_lshl_add_u64 v[56:57], v[48:49], 0, v[138:139]
	v_lshl_add_u64 v[58:59], v[52:53], 0, v[138:139]
	global_load_dwordx4 v[176:179], v[58:59], off
	global_load_dwordx4 v[180:183], v[56:57], off offset:2304
	global_load_dwordx4 v[184:187], v[58:59], off offset:256
	v_add_u32_e32 v200, 0xa0, v140
	v_ashrrev_i32_e32 v201, 31, v200
	v_lshlrev_b64 v[202:203], 12, v[200:201]
	v_lshl_add_u64 v[200:201], s[10:11], 0, v[202:203]
	v_lshl_add_u64 v[204:205], v[200:201], 0, v[138:139]
	global_load_dwordx4 v[188:191], v[204:205], off offset:2048
	s_waitcnt vmcnt(4)
	v_lshlrev_b32_e32 v60, 16, v172
	v_and_b32_e32 v61, 0xffff0000, v172
	s_waitcnt vmcnt(3)
	v_lshlrev_b32_e32 v62, 16, v176
	v_and_b32_e32 v63, 0xffff0000, v176
	v_lshlrev_b32_e32 v48, 16, v173
	v_and_b32_e32 v49, 0xffff0000, v173
	v_lshlrev_b32_e32 v52, 16, v177
	v_and_b32_e32 v53, 0xffff0000, v177
	v_pk_fma_f32 v[46:47], v[46:47], v[48:49], v[52:53]
	v_lshlrev_b32_e32 v48, 16, v174
	v_and_b32_e32 v49, 0xffff0000, v174
	v_lshlrev_b32_e32 v52, 16, v178
	v_and_b32_e32 v53, 0xffff0000, v178
	v_pk_fma_f32 v[48:49], v[40:41], v[48:49], v[52:53]
	v_lshlrev_b32_e32 v40, 16, v175
	v_and_b32_e32 v41, 0xffff0000, v175
	v_lshlrev_b32_e32 v50, 16, v179
	v_and_b32_e32 v51, 0xffff0000, v179
	v_pk_fma_f32 v[44:45], v[44:45], v[60:61], v[62:63]
	v_pk_fma_f32 v[50:51], v[42:43], v[40:41], v[50:51]
	v_cvt_pk_bf16_f32 v40, v44, v45
	v_cvt_pk_bf16_f32 v41, v46, v47
	v_cvt_pk_bf16_f32 v42, v48, v49
	v_cvt_pk_bf16_f32 v43, v50, v51
	global_store_dwordx4 v[58:59], v[40:43], off
	s_nop 0
	s_waitcnt vmcnt(0)
	v_lshlrev_b32_e32 v48, 16, v180
	v_and_b32_e32 v49, 0xffff0000, v180
	s_waitcnt vmcnt(0)
	v_lshlrev_b32_e32 v50, 16, v184
	v_and_b32_e32 v51, 0xffff0000, v184
	v_lshlrev_b32_e32 v40, 16, v181
	v_and_b32_e32 v41, 0xffff0000, v181
	v_lshlrev_b32_e32 v44, 16, v185
	v_and_b32_e32 v45, 0xffff0000, v185
	v_pk_fma_f32 v[38:39], v[38:39], v[40:41], v[44:45]
	v_lshlrev_b32_e32 v40, 16, v182
	v_and_b32_e32 v41, 0xffff0000, v182
	v_lshlrev_b32_e32 v44, 16, v186
	v_and_b32_e32 v45, 0xffff0000, v186
	v_pk_fma_f32 v[40:41], v[32:33], v[40:41], v[44:45]
	v_lshlrev_b32_e32 v32, 16, v183
	v_and_b32_e32 v33, 0xffff0000, v183
	v_lshlrev_b32_e32 v42, 16, v187
	v_and_b32_e32 v43, 0xffff0000, v187
	v_pk_fma_f32 v[36:37], v[36:37], v[48:49], v[50:51]
	v_pk_fma_f32 v[42:43], v[34:35], v[32:33], v[42:43]
	v_cvt_pk_bf16_f32 v32, v36, v37
	v_cvt_pk_bf16_f32 v33, v38, v39
	v_cvt_pk_bf16_f32 v34, v40, v41
	v_cvt_pk_bf16_f32 v35, v42, v43
	global_store_dwordx4 v[58:59], v[32:35], off offset:256
	s_nop 1
	v_add_u32_e32 v32, 0xa0, v140
	v_ashrrev_i32_e32 v33, 31, v32
	v_lshlrev_b64 v[34:35], 12, v[32:33]
	v_lshlrev_b64 v[36:37], 11, v[32:33]
	v_lshl_add_u64 v[32:33], s[10:11], 0, v[34:35]
	v_lshl_add_u64 v[36:37], s[12:13], 0, v[36:37]
	v_lshl_add_u64 v[40:41], v[32:33], 0, v[138:139]
	v_lshl_add_u64 v[42:43], v[36:37], 0, v[138:139]
	global_load_dwordx4 v[192:195], v[42:43], off
	global_load_dwordx4 v[196:199], v[40:41], off offset:2304
	global_load_dwordx4 v[164:167], v[42:43], off offset:256
	v_add_u32_e32 v200, 0xb0, v140
	v_ashrrev_i32_e32 v201, 31, v200
	v_lshlrev_b64 v[202:203], 12, v[200:201]
	v_lshl_add_u64 v[200:201], s[10:11], 0, v[202:203]
	v_lshl_add_u64 v[204:205], v[200:201], 0, v[138:139]
	global_load_dwordx4 v[168:171], v[204:205], off offset:2048
	s_waitcnt vmcnt(4)
	v_lshlrev_b32_e32 v44, 16, v188
	v_and_b32_e32 v45, 0xffff0000, v188
	s_waitcnt vmcnt(3)
	v_lshlrev_b32_e32 v46, 16, v192
	v_and_b32_e32 v47, 0xffff0000, v192
	v_lshlrev_b32_e32 v32, 16, v189
	v_and_b32_e32 v33, 0xffff0000, v189
	v_lshlrev_b32_e32 v36, 16, v193
	v_and_b32_e32 v37, 0xffff0000, v193
	v_pk_fma_f32 v[30:31], v[30:31], v[32:33], v[36:37]
	v_lshlrev_b32_e32 v32, 16, v190
	v_and_b32_e32 v33, 0xffff0000, v190
	v_lshlrev_b32_e32 v36, 16, v194
	v_and_b32_e32 v37, 0xffff0000, v194
	v_pk_fma_f32 v[32:33], v[24:25], v[32:33], v[36:37]
	v_lshlrev_b32_e32 v24, 16, v191
	v_and_b32_e32 v25, 0xffff0000, v191
	v_lshlrev_b32_e32 v34, 16, v195
	v_and_b32_e32 v35, 0xffff0000, v195
	v_pk_fma_f32 v[28:29], v[28:29], v[44:45], v[46:47]
	v_pk_fma_f32 v[34:35], v[26:27], v[24:25], v[34:35]
	v_cvt_pk_bf16_f32 v24, v28, v29
	v_cvt_pk_bf16_f32 v25, v30, v31
	v_cvt_pk_bf16_f32 v26, v32, v33
	v_cvt_pk_bf16_f32 v27, v34, v35
	global_store_dwordx4 v[42:43], v[24:27], off
	s_nop 0
	s_waitcnt vmcnt(0)
	v_lshlrev_b32_e32 v32, 16, v196
	v_and_b32_e32 v33, 0xffff0000, v196
	s_waitcnt vmcnt(0)
	v_lshlrev_b32_e32 v34, 16, v164
	v_and_b32_e32 v35, 0xffff0000, v164
	v_lshlrev_b32_e32 v24, 16, v197
	v_and_b32_e32 v25, 0xffff0000, v197
	v_lshlrev_b32_e32 v28, 16, v165
	v_and_b32_e32 v29, 0xffff0000, v165
	v_pk_fma_f32 v[22:23], v[22:23], v[24:25], v[28:29]
	v_lshlrev_b32_e32 v24, 16, v198
	v_and_b32_e32 v25, 0xffff0000, v198
	v_lshlrev_b32_e32 v28, 16, v166
	v_and_b32_e32 v29, 0xffff0000, v166
	v_pk_fma_f32 v[24:25], v[16:17], v[24:25], v[28:29]
	v_lshlrev_b32_e32 v16, 16, v199
	v_and_b32_e32 v17, 0xffff0000, v199
	v_lshlrev_b32_e32 v26, 16, v167
	v_and_b32_e32 v27, 0xffff0000, v167
	v_pk_fma_f32 v[20:21], v[20:21], v[32:33], v[34:35]
	v_pk_fma_f32 v[26:27], v[18:19], v[16:17], v[26:27]
	v_cvt_pk_bf16_f32 v16, v20, v21
	v_cvt_pk_bf16_f32 v17, v22, v23
	v_cvt_pk_bf16_f32 v18, v24, v25
	v_cvt_pk_bf16_f32 v19, v26, v27
	global_store_dwordx4 v[42:43], v[16:19], off offset:256
	s_nop 1
	v_add_u32_e32 v16, 0xb0, v140
	v_ashrrev_i32_e32 v17, 31, v16
	v_lshlrev_b64 v[18:19], 12, v[16:17]
	v_lshlrev_b64 v[20:21], 11, v[16:17]
	v_lshl_add_u64 v[16:17], s[10:11], 0, v[18:19]
	v_lshl_add_u64 v[20:21], s[12:13], 0, v[20:21]
	v_lshl_add_u64 v[24:25], v[16:17], 0, v[138:139]
	v_lshl_add_u64 v[26:27], v[20:21], 0, v[138:139]
	global_load_dwordx4 v[172:175], v[26:27], off
	global_load_dwordx4 v[176:179], v[24:25], off offset:2304
	global_load_dwordx4 v[180:183], v[26:27], off offset:256
	s_waitcnt vmcnt(3)
	v_lshlrev_b32_e32 v28, 16, v168
	v_and_b32_e32 v29, 0xffff0000, v168
	s_waitcnt vmcnt(2)
	v_lshlrev_b32_e32 v30, 16, v172
	v_and_b32_e32 v31, 0xffff0000, v172
	v_lshlrev_b32_e32 v16, 16, v169
	v_and_b32_e32 v17, 0xffff0000, v169
	v_lshlrev_b32_e32 v20, 16, v173
	v_and_b32_e32 v21, 0xffff0000, v173
	v_pk_fma_f32 v[14:15], v[14:15], v[16:17], v[20:21]
	v_lshlrev_b32_e32 v16, 16, v170
	v_and_b32_e32 v17, 0xffff0000, v170
	v_lshlrev_b32_e32 v20, 16, v174
	v_and_b32_e32 v21, 0xffff0000, v174
	v_pk_fma_f32 v[16:17], v[8:9], v[16:17], v[20:21]
	v_lshlrev_b32_e32 v8, 16, v171
	v_and_b32_e32 v9, 0xffff0000, v171
	v_lshlrev_b32_e32 v18, 16, v175
	v_and_b32_e32 v19, 0xffff0000, v175
	v_pk_fma_f32 v[12:13], v[12:13], v[28:29], v[30:31]
	v_pk_fma_f32 v[18:19], v[10:11], v[8:9], v[18:19]
	v_cvt_pk_bf16_f32 v8, v12, v13
	v_cvt_pk_bf16_f32 v9, v14, v15
	v_cvt_pk_bf16_f32 v10, v16, v17
	v_cvt_pk_bf16_f32 v11, v18, v19
	global_store_dwordx4 v[26:27], v[8:11], off
	s_nop 0
	s_waitcnt vmcnt(0)
	v_lshlrev_b32_e32 v16, 16, v176
	v_and_b32_e32 v17, 0xffff0000, v176
	s_waitcnt vmcnt(0)
	v_lshlrev_b32_e32 v18, 16, v180
	v_and_b32_e32 v19, 0xffff0000, v180
	v_lshlrev_b32_e32 v8, 16, v177
	v_and_b32_e32 v9, 0xffff0000, v177
	v_lshlrev_b32_e32 v12, 16, v181
	v_and_b32_e32 v13, 0xffff0000, v181
	v_pk_fma_f32 v[6:7], v[6:7], v[8:9], v[12:13]
	v_lshlrev_b32_e32 v8, 16, v178
	v_and_b32_e32 v9, 0xffff0000, v178
	v_lshlrev_b32_e32 v12, 16, v182
	v_and_b32_e32 v13, 0xffff0000, v182
	v_pk_fma_f32 v[8:9], v[0:1], v[8:9], v[12:13]
	v_lshlrev_b32_e32 v0, 16, v179
	v_and_b32_e32 v1, 0xffff0000, v179
	v_lshlrev_b32_e32 v10, 16, v183
	v_and_b32_e32 v11, 0xffff0000, v183
	v_pk_fma_f32 v[4:5], v[4:5], v[16:17], v[18:19]
	v_pk_fma_f32 v[10:11], v[2:3], v[0:1], v[10:11]
	v_cvt_pk_bf16_f32 v0, v4, v5
	v_cvt_pk_bf16_f32 v1, v6, v7
	v_cvt_pk_bf16_f32 v2, v8, v9
	v_cvt_pk_bf16_f32 v3, v10, v11
	global_store_dwordx4 v[26:27], v[0:3], off offset:256
	s_cbranch_vccnz .LBB0_1321
	s_andn2_b64 vcc, exec, s[14:15]
	s_cbranch_vccnz .LBB0_1320
	s_barrier
	s_branch .LBB0_1320
